# ret: final-state chunk loop pipelined (3-deep load window, unrolled for 8/2 chunks) and V-fragment LDS reads of the attention loop hoisted ahead of the decay-mask work
# speedup vs baseline: 1.0044x; 1.0044x over previous
.LBB0_342:
	v_and_b32_e32 v77, 63, v0
	v_mov_b32_e32 v18, s69
	v_ashrrev_i32_e32 v19, 5, v0
	v_mad_u32_u24 v18, v77, s62, v18
	v_and_b32_e32 v19, -2, v19
	v_cvt_pk_bf16_f32 v2, v2, s0
	v_add_u32_e32 v19, v18, v19
	v_add_u32_e32 v26, 0x100, v0
	ds_write_b16 v19, v2 offset:54272
	v_cvt_pk_bf16_f32 v2, v3, s0
	v_ashrrev_i32_e32 v3, 5, v26
	v_and_b32_e32 v3, -2, v3
	v_add_u32_e32 v3, v18, v3
	v_add_u32_e32 v42, 0x200, v0
	ds_write_b16 v3, v2 offset:54272
	v_ashrrev_i32_e32 v3, 5, v42
	v_and_b32_e32 v3, -2, v3
	v_cvt_pk_bf16_f32 v2, v4, s0
	v_add_u32_e32 v3, v18, v3
	v_add_u32_e32 v60, 0x300, v0
	ds_write_b16 v3, v2 offset:54272
	v_ashrrev_i32_e32 v3, 5, v60
	v_and_b32_e32 v3, -2, v3
	v_cvt_pk_bf16_f32 v2, v5, s0
	v_add_u32_e32 v3, v18, v3
	ds_write_b16 v3, v2 offset:54272
	v_add_u32_e32 v2, 0x400, v0
	v_ashrrev_i32_e32 v2, 5, v2
	v_and_b32_e32 v2, -2, v2
	v_cvt_pk_bf16_f32 v3, v6, s0
	v_add_u32_e32 v2, v18, v2
	ds_write_b16 v2, v3 offset:54272
	v_add_u32_e32 v2, 0x500, v0
	v_ashrrev_i32_e32 v2, 5, v2
	v_and_b32_e32 v2, -2, v2
	v_cvt_pk_bf16_f32 v3, v7, s0
	v_add_u32_e32 v2, v18, v2
	ds_write_b16 v2, v3 offset:54272
	v_add_u32_e32 v2, 0x600, v0
	v_ashrrev_i32_e32 v2, 5, v2
	v_and_b32_e32 v2, -2, v2
	v_cvt_pk_bf16_f32 v3, v8, s0
	v_add_u32_e32 v2, v18, v2
	ds_write_b16 v2, v3 offset:54272
	v_add_u32_e32 v2, 0x700, v0
	v_ashrrev_i32_e32 v2, 5, v2
	v_and_b32_e32 v2, -2, v2
	v_cvt_pk_bf16_f32 v3, v9, s0
	v_add_u32_e32 v2, v18, v2
	ds_write_b16 v2, v3 offset:54272
	v_add_u32_e32 v2, 0x800, v0
	v_ashrrev_i32_e32 v2, 5, v2
	v_and_b32_e32 v2, -2, v2
	v_cvt_pk_bf16_f32 v3, v10, s0
	v_add_u32_e32 v2, v18, v2
	ds_write_b16 v2, v3 offset:54272
	v_add_u32_e32 v2, 0x900, v0
	v_ashrrev_i32_e32 v2, 5, v2
	v_and_b32_e32 v2, -2, v2
	v_cvt_pk_bf16_f32 v3, v11, s0
	v_add_u32_e32 v2, v18, v2
	ds_write_b16 v2, v3 offset:54272
	v_add_u32_e32 v2, 0xa00, v0
	v_ashrrev_i32_e32 v2, 5, v2
	v_and_b32_e32 v2, -2, v2
	v_cvt_pk_bf16_f32 v3, v12, s0
	v_add_u32_e32 v2, v18, v2
	ds_write_b16 v2, v3 offset:54272
	v_add_u32_e32 v2, 0xb00, v0
	v_ashrrev_i32_e32 v2, 5, v2
	v_and_b32_e32 v2, -2, v2
	v_cvt_pk_bf16_f32 v3, v13, s0
	v_add_u32_e32 v2, v18, v2
	ds_write_b16 v2, v3 offset:54272
	v_add_u32_e32 v2, 0xc00, v0
	v_ashrrev_i32_e32 v2, 5, v2
	v_and_b32_e32 v2, -2, v2
	v_cvt_pk_bf16_f32 v3, v14, s0
	v_add_u32_e32 v2, v18, v2
	ds_write_b16 v2, v3 offset:54272
	v_add_u32_e32 v2, 0xd00, v0
	v_ashrrev_i32_e32 v2, 5, v2
	v_and_b32_e32 v2, -2, v2
	v_cvt_pk_bf16_f32 v3, v15, s0
	v_add_u32_e32 v2, v18, v2
	ds_write_b16 v2, v3 offset:54272
	v_add_u32_e32 v2, 0xe00, v0
	v_ashrrev_i32_e32 v2, 5, v2
	v_and_b32_e32 v2, -2, v2
	s_lshl_b32 s44, s57, 6
	v_cvt_pk_bf16_f32 v3, v16, s0
	v_add_u32_e32 v2, v18, v2
	ds_write_b16 v2, v3 offset:54272
	v_add_u32_e32 v2, 0xf00, v0
	s_cmpk_gt_u32 s56, 0x7f
	v_ashrrev_i32_e32 v2, 5, v2
	s_cselect_b64 s[38:39], -1, 0
	v_and_b32_e32 v2, -2, v2
	s_or_b64 s[2:3], s[2:3], s[38:39]
	v_cvt_pk_bf16_f32 v3, v17, s0
	v_add_u32_e32 v2, v18, v2
	s_andn2_b64 vcc, exec, s[2:3]
	ds_write_b16 v2, v3 offset:54272
	s_cbranch_vccz .LBB0_346
	s_and_b32 s2, s52, 3
	s_lshl_b32 s3, s29, 3
	s_lshl_b32 s2, s2, 1
	s_add_i32 s3, s90, s3
	v_mov_b32_e32 v2, 0
	v_lshl_add_u64 v[18:19], v[0:1], 2, s[26:27]
	s_add_i32 s28, s28, -1
	s_add_i32 s2, s3, s2
	s_mov_b32 s38, 0
	v_mov_b32_e32 v3, v2
	v_mov_b32_e32 v16, v2
	v_mov_b32_e32 v17, v2
	v_mov_b32_e32 v14, v2
	v_mov_b32_e32 v15, v2
	v_mov_b32_e32 v12, v2
	v_mov_b32_e32 v13, v2
	v_mov_b32_e32 v10, v2
	v_mov_b32_e32 v11, v2
	v_mov_b32_e32 v8, v2
	v_mov_b32_e32 v9, v2
	v_mov_b32_e32 v6, v2
	v_mov_b32_e32 v7, v2
	v_mov_b32_e32 v4, v2
	v_mov_b32_e32 v5, v2
	s_cmp_eq_u32 s28, 7
	s_cbranch_scc1 .Lso8
	s_cmp_eq_u32 s28, 1
	s_cbranch_scc1 .Lso2
.LBB0_344:
	s_and_b64 s[40:41], s[36:37], exec
	s_cselect_b32 s3, s28, s38
	v_cvt_f32_i32_e32 v20, s3
	s_ashr_i32 s3, s2, 31
	s_lshl_b64 s[40:41], s[2:3], 14
	v_lshl_add_u64 v[22:23], v[18:19], 0, s[40:41]
	v_add_co_u32_e32 v24, vcc, s93, v22
	s_nop 1
	v_addc_co_u32_e32 v25, vcc, 0, v23, vcc
	v_add_co_u32_e32 v28, vcc, s31, v22
	s_nop 1
	v_addc_co_u32_e32 v29, vcc, 0, v23, vcc
	global_load_dword v128, v[22:23], off
	global_load_dword v129, v[22:23], off offset:1024
	global_load_dword v130, v[22:23], off offset:2048
	global_load_dword v131, v[22:23], off offset:3072
	v_add_co_u32_e32 v22, vcc, s63, v22
	s_nop 1
	v_addc_co_u32_e32 v23, vcc, 0, v23, vcc
	global_load_dword v132, v[24:25], off
	global_load_dword v133, v[24:25], off offset:1024
	global_load_dword v134, v[24:25], off offset:2048
	global_load_dword v135, v[24:25], off offset:3072
	global_load_dword v136, v[28:29], off
	global_load_dword v137, v[28:29], off offset:1024
	global_load_dword v138, v[28:29], off offset:2048
	global_load_dword v139, v[28:29], off offset:3072
	global_load_dword v140, v[22:23], off
	global_load_dword v141, v[22:23], off offset:1024
	global_load_dword v142, v[22:23], off offset:2048
	global_load_dword v143, v[22:23], off offset:3072
	v_mul_f32_e32 v20, v71, v20
	v_mul_f32_e32 v20, 0x3fb8aa3b, v20
	v_exp_f32_e32 v20, v20
	s_add_i32 s38, s38, 1
	s_add_i32 s28, s28, -1
	s_add_i32 s2, s2, 8
	s_cmp_eq_u32 s28, -1
	s_waitcnt vmcnt(0)
	v_pk_fma_f32 v[16:17], v[128:129], v[20:21], v[16:17] op_sel_hi:[1,0,1]
	v_pk_fma_f32 v[14:15], v[130:131], v[20:21], v[14:15] op_sel_hi:[1,0,1]
	v_pk_fma_f32 v[12:13], v[20:21], v[132:133], v[12:13] op_sel_hi:[0,1,1]
	v_pk_fma_f32 v[10:11], v[20:21], v[134:135], v[10:11] op_sel_hi:[0,1,1]
	v_pk_fma_f32 v[8:9], v[20:21], v[136:137], v[8:9] op_sel_hi:[0,1,1]
	v_pk_fma_f32 v[6:7], v[20:21], v[138:139], v[6:7] op_sel_hi:[0,1,1]
	v_pk_fma_f32 v[4:5], v[20:21], v[140:141], v[4:5] op_sel_hi:[0,1,1]
	v_pk_fma_f32 v[2:3], v[20:21], v[142:143], v[2:3] op_sel_hi:[0,1,1]
	s_cbranch_scc0 .LBB0_344
	s_branch .Lso_done
.Lso8:
	s_mov_b64 s[96:97], 0x1000
	s_ashr_i32 s3, s2, 31
	s_lshl_b64 s[40:41], s[2:3], 14
	v_lshl_add_u64 v[22:23], v[18:19], 0, s[40:41]
	v_lshl_add_u64 v[24:25], v[22:23], 0, s[96:97]
	v_lshl_add_u64 v[28:29], v[24:25], 0, s[96:97]
	v_lshl_add_u64 v[26:27], v[28:29], 0, s[96:97]
	global_load_dword v128, v[22:23], off
	global_load_dword v129, v[22:23], off offset:1024
	global_load_dword v130, v[22:23], off offset:2048
	global_load_dword v131, v[22:23], off offset:3072
	global_load_dword v132, v[24:25], off
	global_load_dword v133, v[24:25], off offset:1024
	global_load_dword v134, v[24:25], off offset:2048
	global_load_dword v135, v[24:25], off offset:3072
	global_load_dword v136, v[28:29], off
	global_load_dword v137, v[28:29], off offset:1024
	global_load_dword v138, v[28:29], off offset:2048
	global_load_dword v139, v[28:29], off offset:3072
	global_load_dword v140, v[26:27], off
	global_load_dword v141, v[26:27], off offset:1024
	global_load_dword v142, v[26:27], off offset:2048
	global_load_dword v143, v[26:27], off offset:3072
	s_add_i32 s2, s2, 8
	s_ashr_i32 s3, s2, 31
	s_lshl_b64 s[40:41], s[2:3], 14
	v_lshl_add_u64 v[22:23], v[18:19], 0, s[40:41]
	v_lshl_add_u64 v[24:25], v[22:23], 0, s[96:97]
	v_lshl_add_u64 v[28:29], v[24:25], 0, s[96:97]
	v_lshl_add_u64 v[26:27], v[28:29], 0, s[96:97]
	global_load_dword v144, v[22:23], off
	global_load_dword v145, v[22:23], off offset:1024
	global_load_dword v146, v[22:23], off offset:2048
	global_load_dword v147, v[22:23], off offset:3072
	global_load_dword v148, v[24:25], off
	global_load_dword v149, v[24:25], off offset:1024
	global_load_dword v150, v[24:25], off offset:2048
	global_load_dword v151, v[24:25], off offset:3072
	global_load_dword v152, v[28:29], off
	global_load_dword v153, v[28:29], off offset:1024
	global_load_dword v154, v[28:29], off offset:2048
	global_load_dword v155, v[28:29], off offset:3072
	global_load_dword v156, v[26:27], off
	global_load_dword v157, v[26:27], off offset:1024
	global_load_dword v158, v[26:27], off offset:2048
	global_load_dword v159, v[26:27], off offset:3072
	s_add_i32 s2, s2, 8
	s_ashr_i32 s3, s2, 31
	s_lshl_b64 s[40:41], s[2:3], 14
	v_lshl_add_u64 v[22:23], v[18:19], 0, s[40:41]
	v_lshl_add_u64 v[24:25], v[22:23], 0, s[96:97]
	v_lshl_add_u64 v[28:29], v[24:25], 0, s[96:97]
	v_lshl_add_u64 v[26:27], v[28:29], 0, s[96:97]
	global_load_dword v160, v[22:23], off
	global_load_dword v161, v[22:23], off offset:1024
	global_load_dword v162, v[22:23], off offset:2048
	global_load_dword v163, v[22:23], off offset:3072
	global_load_dword v164, v[24:25], off
	global_load_dword v165, v[24:25], off offset:1024
	global_load_dword v166, v[24:25], off offset:2048
	global_load_dword v167, v[24:25], off offset:3072
	global_load_dword v168, v[28:29], off
	global_load_dword v169, v[28:29], off offset:1024
	global_load_dword v170, v[28:29], off offset:2048
	global_load_dword v171, v[28:29], off offset:3072
	global_load_dword v172, v[26:27], off
	global_load_dword v173, v[26:27], off offset:1024
	global_load_dword v174, v[26:27], off offset:2048
	global_load_dword v175, v[26:27], off offset:3072
	s_add_i32 s2, s2, 8
	s_and_b64 s[40:41], s[36:37], exec
	s_cselect_b32 s3, 7, 0
	v_cvt_f32_i32_e32 v20, s3
	v_mul_f32_e32 v20, v71, v20
	v_mul_f32_e32 v20, 0x3fb8aa3b, v20
	v_exp_f32_e32 v20, v20
	s_waitcnt vmcnt(32)
	s_nop 0
	v_pk_fma_f32 v[16:17], v[128:129], v[20:21], v[16:17] op_sel_hi:[1,0,1]
	v_pk_fma_f32 v[14:15], v[130:131], v[20:21], v[14:15] op_sel_hi:[1,0,1]
	v_pk_fma_f32 v[12:13], v[20:21], v[132:133], v[12:13] op_sel_hi:[0,1,1]
	v_pk_fma_f32 v[10:11], v[20:21], v[134:135], v[10:11] op_sel_hi:[0,1,1]
	v_pk_fma_f32 v[8:9], v[20:21], v[136:137], v[8:9] op_sel_hi:[0,1,1]
	v_pk_fma_f32 v[6:7], v[20:21], v[138:139], v[6:7] op_sel_hi:[0,1,1]
	v_pk_fma_f32 v[4:5], v[20:21], v[140:141], v[4:5] op_sel_hi:[0,1,1]
	v_pk_fma_f32 v[2:3], v[20:21], v[142:143], v[2:3] op_sel_hi:[0,1,1]
	s_ashr_i32 s3, s2, 31
	s_lshl_b64 s[40:41], s[2:3], 14
	v_lshl_add_u64 v[22:23], v[18:19], 0, s[40:41]
	v_lshl_add_u64 v[24:25], v[22:23], 0, s[96:97]
	v_lshl_add_u64 v[28:29], v[24:25], 0, s[96:97]
	v_lshl_add_u64 v[26:27], v[28:29], 0, s[96:97]
	global_load_dword v176, v[22:23], off
	global_load_dword v177, v[22:23], off offset:1024
	global_load_dword v178, v[22:23], off offset:2048
	global_load_dword v179, v[22:23], off offset:3072
	global_load_dword v180, v[24:25], off
	global_load_dword v181, v[24:25], off offset:1024
	global_load_dword v182, v[24:25], off offset:2048
	global_load_dword v183, v[24:25], off offset:3072
	global_load_dword v184, v[28:29], off
	global_load_dword v185, v[28:29], off offset:1024
	global_load_dword v186, v[28:29], off offset:2048
	global_load_dword v187, v[28:29], off offset:3072
	global_load_dword v188, v[26:27], off
	global_load_dword v189, v[26:27], off offset:1024
	global_load_dword v190, v[26:27], off offset:2048
	global_load_dword v191, v[26:27], off offset:3072
	s_add_i32 s2, s2, 8
	s_and_b64 s[40:41], s[36:37], exec
	s_cselect_b32 s3, 6, 1
	v_cvt_f32_i32_e32 v20, s3
	v_mul_f32_e32 v20, v71, v20
	v_mul_f32_e32 v20, 0x3fb8aa3b, v20
	v_exp_f32_e32 v20, v20
	s_waitcnt vmcnt(32)
	s_nop 0
	v_pk_fma_f32 v[16:17], v[144:145], v[20:21], v[16:17] op_sel_hi:[1,0,1]
	v_pk_fma_f32 v[14:15], v[146:147], v[20:21], v[14:15] op_sel_hi:[1,0,1]
	v_pk_fma_f32 v[12:13], v[20:21], v[148:149], v[12:13] op_sel_hi:[0,1,1]
	v_pk_fma_f32 v[10:11], v[20:21], v[150:151], v[10:11] op_sel_hi:[0,1,1]
	v_pk_fma_f32 v[8:9], v[20:21], v[152:153], v[8:9] op_sel_hi:[0,1,1]
	v_pk_fma_f32 v[6:7], v[20:21], v[154:155], v[6:7] op_sel_hi:[0,1,1]
	v_pk_fma_f32 v[4:5], v[20:21], v[156:157], v[4:5] op_sel_hi:[0,1,1]
	v_pk_fma_f32 v[2:3], v[20:21], v[158:159], v[2:3] op_sel_hi:[0,1,1]
	s_ashr_i32 s3, s2, 31
	s_lshl_b64 s[40:41], s[2:3], 14
	v_lshl_add_u64 v[22:23], v[18:19], 0, s[40:41]
	v_lshl_add_u64 v[24:25], v[22:23], 0, s[96:97]
	v_lshl_add_u64 v[28:29], v[24:25], 0, s[96:97]
	v_lshl_add_u64 v[26:27], v[28:29], 0, s[96:97]
	global_load_dword v128, v[22:23], off
	global_load_dword v129, v[22:23], off offset:1024
	global_load_dword v130, v[22:23], off offset:2048
	global_load_dword v131, v[22:23], off offset:3072
	global_load_dword v132, v[24:25], off
	global_load_dword v133, v[24:25], off offset:1024
	global_load_dword v134, v[24:25], off offset:2048
	global_load_dword v135, v[24:25], off offset:3072
	global_load_dword v136, v[28:29], off
	global_load_dword v137, v[28:29], off offset:1024
	global_load_dword v138, v[28:29], off offset:2048
	global_load_dword v139, v[28:29], off offset:3072
	global_load_dword v140, v[26:27], off
	global_load_dword v141, v[26:27], off offset:1024
	global_load_dword v142, v[26:27], off offset:2048
	global_load_dword v143, v[26:27], off offset:3072
	s_add_i32 s2, s2, 8
	s_and_b64 s[40:41], s[36:37], exec
	s_cselect_b32 s3, 5, 2
	v_cvt_f32_i32_e32 v20, s3
	v_mul_f32_e32 v20, v71, v20
	v_mul_f32_e32 v20, 0x3fb8aa3b, v20
	v_exp_f32_e32 v20, v20
	s_waitcnt vmcnt(32)
	s_nop 0
	v_pk_fma_f32 v[16:17], v[160:161], v[20:21], v[16:17] op_sel_hi:[1,0,1]
	v_pk_fma_f32 v[14:15], v[162:163], v[20:21], v[14:15] op_sel_hi:[1,0,1]
	v_pk_fma_f32 v[12:13], v[20:21], v[164:165], v[12:13] op_sel_hi:[0,1,1]
	v_pk_fma_f32 v[10:11], v[20:21], v[166:167], v[10:11] op_sel_hi:[0,1,1]
	v_pk_fma_f32 v[8:9], v[20:21], v[168:169], v[8:9] op_sel_hi:[0,1,1]
	v_pk_fma_f32 v[6:7], v[20:21], v[170:171], v[6:7] op_sel_hi:[0,1,1]
	v_pk_fma_f32 v[4:5], v[20:21], v[172:173], v[4:5] op_sel_hi:[0,1,1]
	v_pk_fma_f32 v[2:3], v[20:21], v[174:175], v[2:3] op_sel_hi:[0,1,1]
	s_ashr_i32 s3, s2, 31
	s_lshl_b64 s[40:41], s[2:3], 14
	v_lshl_add_u64 v[22:23], v[18:19], 0, s[40:41]
	v_lshl_add_u64 v[24:25], v[22:23], 0, s[96:97]
	v_lshl_add_u64 v[28:29], v[24:25], 0, s[96:97]
	v_lshl_add_u64 v[26:27], v[28:29], 0, s[96:97]
	global_load_dword v144, v[22:23], off
	global_load_dword v145, v[22:23], off offset:1024
	global_load_dword v146, v[22:23], off offset:2048
	global_load_dword v147, v[22:23], off offset:3072
	global_load_dword v148, v[24:25], off
	global_load_dword v149, v[24:25], off offset:1024
	global_load_dword v150, v[24:25], off offset:2048
	global_load_dword v151, v[24:25], off offset:3072
	global_load_dword v152, v[28:29], off
	global_load_dword v153, v[28:29], off offset:1024
	global_load_dword v154, v[28:29], off offset:2048
	global_load_dword v155, v[28:29], off offset:3072
	global_load_dword v156, v[26:27], off
	global_load_dword v157, v[26:27], off offset:1024
	global_load_dword v158, v[26:27], off offset:2048
	global_load_dword v159, v[26:27], off offset:3072
	s_add_i32 s2, s2, 8
	s_and_b64 s[40:41], s[36:37], exec
	s_cselect_b32 s3, 4, 3
	v_cvt_f32_i32_e32 v20, s3
	v_mul_f32_e32 v20, v71, v20
	v_mul_f32_e32 v20, 0x3fb8aa3b, v20
	v_exp_f32_e32 v20, v20
	s_waitcnt vmcnt(32)
	s_nop 0
	v_pk_fma_f32 v[16:17], v[176:177], v[20:21], v[16:17] op_sel_hi:[1,0,1]
	v_pk_fma_f32 v[14:15], v[178:179], v[20:21], v[14:15] op_sel_hi:[1,0,1]
	v_pk_fma_f32 v[12:13], v[20:21], v[180:181], v[12:13] op_sel_hi:[0,1,1]
	v_pk_fma_f32 v[10:11], v[20:21], v[182:183], v[10:11] op_sel_hi:[0,1,1]
	v_pk_fma_f32 v[8:9], v[20:21], v[184:185], v[8:9] op_sel_hi:[0,1,1]
	v_pk_fma_f32 v[6:7], v[20:21], v[186:187], v[6:7] op_sel_hi:[0,1,1]
	v_pk_fma_f32 v[4:5], v[20:21], v[188:189], v[4:5] op_sel_hi:[0,1,1]
	v_pk_fma_f32 v[2:3], v[20:21], v[190:191], v[2:3] op_sel_hi:[0,1,1]
	s_ashr_i32 s3, s2, 31
	s_lshl_b64 s[40:41], s[2:3], 14
	v_lshl_add_u64 v[22:23], v[18:19], 0, s[40:41]
	v_lshl_add_u64 v[24:25], v[22:23], 0, s[96:97]
	v_lshl_add_u64 v[28:29], v[24:25], 0, s[96:97]
	v_lshl_add_u64 v[26:27], v[28:29], 0, s[96:97]
	global_load_dword v160, v[22:23], off
	global_load_dword v161, v[22:23], off offset:1024
	global_load_dword v162, v[22:23], off offset:2048
	global_load_dword v163, v[22:23], off offset:3072
	global_load_dword v164, v[24:25], off
	global_load_dword v165, v[24:25], off offset:1024
	global_load_dword v166, v[24:25], off offset:2048
	global_load_dword v167, v[24:25], off offset:3072
	global_load_dword v168, v[28:29], off
	global_load_dword v169, v[28:29], off offset:1024
	global_load_dword v170, v[28:29], off offset:2048
	global_load_dword v171, v[28:29], off offset:3072
	global_load_dword v172, v[26:27], off
	global_load_dword v173, v[26:27], off offset:1024
	global_load_dword v174, v[26:27], off offset:2048
	global_load_dword v175, v[26:27], off offset:3072
	s_add_i32 s2, s2, 8
	s_and_b64 s[40:41], s[36:37], exec
	s_cselect_b32 s3, 3, 4
	v_cvt_f32_i32_e32 v20, s3
	v_mul_f32_e32 v20, v71, v20
	v_mul_f32_e32 v20, 0x3fb8aa3b, v20
	v_exp_f32_e32 v20, v20
	s_waitcnt vmcnt(32)
	s_nop 0
	v_pk_fma_f32 v[16:17], v[128:129], v[20:21], v[16:17] op_sel_hi:[1,0,1]
	v_pk_fma_f32 v[14:15], v[130:131], v[20:21], v[14:15] op_sel_hi:[1,0,1]
	v_pk_fma_f32 v[12:13], v[20:21], v[132:133], v[12:13] op_sel_hi:[0,1,1]
	v_pk_fma_f32 v[10:11], v[20:21], v[134:135], v[10:11] op_sel_hi:[0,1,1]
	v_pk_fma_f32 v[8:9], v[20:21], v[136:137], v[8:9] op_sel_hi:[0,1,1]
	v_pk_fma_f32 v[6:7], v[20:21], v[138:139], v[6:7] op_sel_hi:[0,1,1]
	v_pk_fma_f32 v[4:5], v[20:21], v[140:141], v[4:5] op_sel_hi:[0,1,1]
	v_pk_fma_f32 v[2:3], v[20:21], v[142:143], v[2:3] op_sel_hi:[0,1,1]
	s_ashr_i32 s3, s2, 31
	s_lshl_b64 s[40:41], s[2:3], 14
	v_lshl_add_u64 v[22:23], v[18:19], 0, s[40:41]
	v_lshl_add_u64 v[24:25], v[22:23], 0, s[96:97]
	v_lshl_add_u64 v[28:29], v[24:25], 0, s[96:97]
	v_lshl_add_u64 v[26:27], v[28:29], 0, s[96:97]
	global_load_dword v176, v[22:23], off
	global_load_dword v177, v[22:23], off offset:1024
	global_load_dword v178, v[22:23], off offset:2048
	global_load_dword v179, v[22:23], off offset:3072
	global_load_dword v180, v[24:25], off
	global_load_dword v181, v[24:25], off offset:1024
	global_load_dword v182, v[24:25], off offset:2048
	global_load_dword v183, v[24:25], off offset:3072
	global_load_dword v184, v[28:29], off
	global_load_dword v185, v[28:29], off offset:1024
	global_load_dword v186, v[28:29], off offset:2048
	global_load_dword v187, v[28:29], off offset:3072
	global_load_dword v188, v[26:27], off
	global_load_dword v189, v[26:27], off offset:1024
	global_load_dword v190, v[26:27], off offset:2048
	global_load_dword v191, v[26:27], off offset:3072
	s_add_i32 s2, s2, 8
	s_and_b64 s[40:41], s[36:37], exec
	s_cselect_b32 s3, 2, 5
	v_cvt_f32_i32_e32 v20, s3
	v_mul_f32_e32 v20, v71, v20
	v_mul_f32_e32 v20, 0x3fb8aa3b, v20
	v_exp_f32_e32 v20, v20
	s_waitcnt vmcnt(32)
	s_nop 0
	v_pk_fma_f32 v[16:17], v[144:145], v[20:21], v[16:17] op_sel_hi:[1,0,1]
	v_pk_fma_f32 v[14:15], v[146:147], v[20:21], v[14:15] op_sel_hi:[1,0,1]
	v_pk_fma_f32 v[12:13], v[20:21], v[148:149], v[12:13] op_sel_hi:[0,1,1]
	v_pk_fma_f32 v[10:11], v[20:21], v[150:151], v[10:11] op_sel_hi:[0,1,1]
	v_pk_fma_f32 v[8:9], v[20:21], v[152:153], v[8:9] op_sel_hi:[0,1,1]
	v_pk_fma_f32 v[6:7], v[20:21], v[154:155], v[6:7] op_sel_hi:[0,1,1]
	v_pk_fma_f32 v[4:5], v[20:21], v[156:157], v[4:5] op_sel_hi:[0,1,1]
	v_pk_fma_f32 v[2:3], v[20:21], v[158:159], v[2:3] op_sel_hi:[0,1,1]
	s_and_b64 s[40:41], s[36:37], exec
	s_cselect_b32 s3, 1, 6
	v_cvt_f32_i32_e32 v20, s3
	v_mul_f32_e32 v20, v71, v20
	v_mul_f32_e32 v20, 0x3fb8aa3b, v20
	v_exp_f32_e32 v20, v20
	s_waitcnt vmcnt(16)
	s_nop 0
	v_pk_fma_f32 v[16:17], v[160:161], v[20:21], v[16:17] op_sel_hi:[1,0,1]
	v_pk_fma_f32 v[14:15], v[162:163], v[20:21], v[14:15] op_sel_hi:[1,0,1]
	v_pk_fma_f32 v[12:13], v[20:21], v[164:165], v[12:13] op_sel_hi:[0,1,1]
	v_pk_fma_f32 v[10:11], v[20:21], v[166:167], v[10:11] op_sel_hi:[0,1,1]
	v_pk_fma_f32 v[8:9], v[20:21], v[168:169], v[8:9] op_sel_hi:[0,1,1]
	v_pk_fma_f32 v[6:7], v[20:21], v[170:171], v[6:7] op_sel_hi:[0,1,1]
	v_pk_fma_f32 v[4:5], v[20:21], v[172:173], v[4:5] op_sel_hi:[0,1,1]
	v_pk_fma_f32 v[2:3], v[20:21], v[174:175], v[2:3] op_sel_hi:[0,1,1]
	s_and_b64 s[40:41], s[36:37], exec
	s_cselect_b32 s3, 0, 7
	v_cvt_f32_i32_e32 v20, s3
	v_mul_f32_e32 v20, v71, v20
	v_mul_f32_e32 v20, 0x3fb8aa3b, v20
	v_exp_f32_e32 v20, v20
	s_waitcnt vmcnt(0)
	s_nop 0
	v_pk_fma_f32 v[16:17], v[176:177], v[20:21], v[16:17] op_sel_hi:[1,0,1]
	v_pk_fma_f32 v[14:15], v[178:179], v[20:21], v[14:15] op_sel_hi:[1,0,1]
	v_pk_fma_f32 v[12:13], v[20:21], v[180:181], v[12:13] op_sel_hi:[0,1,1]
	v_pk_fma_f32 v[10:11], v[20:21], v[182:183], v[10:11] op_sel_hi:[0,1,1]
	v_pk_fma_f32 v[8:9], v[20:21], v[184:185], v[8:9] op_sel_hi:[0,1,1]
	v_pk_fma_f32 v[6:7], v[20:21], v[186:187], v[6:7] op_sel_hi:[0,1,1]
	v_pk_fma_f32 v[4:5], v[20:21], v[188:189], v[4:5] op_sel_hi:[0,1,1]
	v_pk_fma_f32 v[2:3], v[20:21], v[190:191], v[2:3] op_sel_hi:[0,1,1]
	s_branch .Lso_done
.Lso2:
	s_mov_b64 s[96:97], 0x1000
	s_ashr_i32 s3, s2, 31
	s_lshl_b64 s[40:41], s[2:3], 14
	v_lshl_add_u64 v[22:23], v[18:19], 0, s[40:41]
	v_lshl_add_u64 v[24:25], v[22:23], 0, s[96:97]
	v_lshl_add_u64 v[28:29], v[24:25], 0, s[96:97]
	v_lshl_add_u64 v[26:27], v[28:29], 0, s[96:97]
	global_load_dword v128, v[22:23], off
	global_load_dword v129, v[22:23], off offset:1024
	global_load_dword v130, v[22:23], off offset:2048
	global_load_dword v131, v[22:23], off offset:3072
	global_load_dword v132, v[24:25], off
	global_load_dword v133, v[24:25], off offset:1024
	global_load_dword v134, v[24:25], off offset:2048
	global_load_dword v135, v[24:25], off offset:3072
	global_load_dword v136, v[28:29], off
	global_load_dword v137, v[28:29], off offset:1024
	global_load_dword v138, v[28:29], off offset:2048
	global_load_dword v139, v[28:29], off offset:3072
	global_load_dword v140, v[26:27], off
	global_load_dword v141, v[26:27], off offset:1024
	global_load_dword v142, v[26:27], off offset:2048
	global_load_dword v143, v[26:27], off offset:3072
	s_add_i32 s2, s2, 8
	s_ashr_i32 s3, s2, 31
	s_lshl_b64 s[40:41], s[2:3], 14
	v_lshl_add_u64 v[22:23], v[18:19], 0, s[40:41]
	v_lshl_add_u64 v[24:25], v[22:23], 0, s[96:97]
	v_lshl_add_u64 v[28:29], v[24:25], 0, s[96:97]
	v_lshl_add_u64 v[26:27], v[28:29], 0, s[96:97]
	global_load_dword v144, v[22:23], off
	global_load_dword v145, v[22:23], off offset:1024
	global_load_dword v146, v[22:23], off offset:2048
	global_load_dword v147, v[22:23], off offset:3072
	global_load_dword v148, v[24:25], off
	global_load_dword v149, v[24:25], off offset:1024
	global_load_dword v150, v[24:25], off offset:2048
	global_load_dword v151, v[24:25], off offset:3072
	global_load_dword v152, v[28:29], off
	global_load_dword v153, v[28:29], off offset:1024
	global_load_dword v154, v[28:29], off offset:2048
	global_load_dword v155, v[28:29], off offset:3072
	global_load_dword v156, v[26:27], off
	global_load_dword v157, v[26:27], off offset:1024
	global_load_dword v158, v[26:27], off offset:2048
	global_load_dword v159, v[26:27], off offset:3072
	s_add_i32 s2, s2, 8
	s_and_b64 s[40:41], s[36:37], exec
	s_cselect_b32 s3, 1, 0
	v_cvt_f32_i32_e32 v20, s3
	v_mul_f32_e32 v20, v71, v20
	v_mul_f32_e32 v20, 0x3fb8aa3b, v20
	v_exp_f32_e32 v20, v20
	s_waitcnt vmcnt(16)
	s_nop 0
	v_pk_fma_f32 v[16:17], v[128:129], v[20:21], v[16:17] op_sel_hi:[1,0,1]
	v_pk_fma_f32 v[14:15], v[130:131], v[20:21], v[14:15] op_sel_hi:[1,0,1]
	v_pk_fma_f32 v[12:13], v[20:21], v[132:133], v[12:13] op_sel_hi:[0,1,1]
	v_pk_fma_f32 v[10:11], v[20:21], v[134:135], v[10:11] op_sel_hi:[0,1,1]
	v_pk_fma_f32 v[8:9], v[20:21], v[136:137], v[8:9] op_sel_hi:[0,1,1]
	v_pk_fma_f32 v[6:7], v[20:21], v[138:139], v[6:7] op_sel_hi:[0,1,1]
	v_pk_fma_f32 v[4:5], v[20:21], v[140:141], v[4:5] op_sel_hi:[0,1,1]
	v_pk_fma_f32 v[2:3], v[20:21], v[142:143], v[2:3] op_sel_hi:[0,1,1]
	s_and_b64 s[40:41], s[36:37], exec
	s_cselect_b32 s3, 0, 1
	v_cvt_f32_i32_e32 v20, s3
	v_mul_f32_e32 v20, v71, v20
	v_mul_f32_e32 v20, 0x3fb8aa3b, v20
	v_exp_f32_e32 v20, v20
	s_waitcnt vmcnt(0)
	s_nop 0
	v_pk_fma_f32 v[16:17], v[144:145], v[20:21], v[16:17] op_sel_hi:[1,0,1]
	v_pk_fma_f32 v[14:15], v[146:147], v[20:21], v[14:15] op_sel_hi:[1,0,1]
	v_pk_fma_f32 v[12:13], v[20:21], v[148:149], v[12:13] op_sel_hi:[0,1,1]
	v_pk_fma_f32 v[10:11], v[20:21], v[150:151], v[10:11] op_sel_hi:[0,1,1]
	v_pk_fma_f32 v[8:9], v[20:21], v[152:153], v[8:9] op_sel_hi:[0,1,1]
	v_pk_fma_f32 v[6:7], v[20:21], v[154:155], v[6:7] op_sel_hi:[0,1,1]
	v_pk_fma_f32 v[4:5], v[20:21], v[156:157], v[4:5] op_sel_hi:[0,1,1]
	v_pk_fma_f32 v[2:3], v[20:21], v[158:159], v[2:3] op_sel_hi:[0,1,1]
.Lso_done:
	s_and_b32 s2, s29, 0x1ffffffe
	v_readlane_b32 s28, v255, 36
	s_add_i32 s2, s2, s28
	s_lshl_b32 s2, s2, 3
	s_add_i32 s2, s2, s46
	s_or_b32 s2, s2, s57
	s_ashr_i32 s3, s2, 31
	s_lshl_b64 s[2:3], s[2:3], 14
	v_readlane_b32 s28, v254, 54
	s_add_u32 s2, s28, s2
	v_readlane_b32 s28, v254, 55
	s_addc_u32 s3, s28, s3
	v_lshl_add_u64 v[18:19], v[0:1], 2, s[2:3]
	global_store_dword v[18:19], v16, off
	global_store_dword v[18:19], v17, off offset:1024
	global_store_dword v[18:19], v14, off offset:2048
	global_store_dword v[18:19], v15, off offset:3072
	v_add_co_u32_e32 v14, vcc, s93, v18
	v_readlane_b32 s29, v255, 37
	s_nop 0
	v_addc_co_u32_e32 v15, vcc, 0, v19, vcc
	v_add_co_u32_e32 v16, vcc, s31, v18
	s_nop 1
	v_addc_co_u32_e32 v17, vcc, 0, v19, vcc
	global_store_dword v[16:17], v12, off offset:-4096
	global_store_dword v[14:15], v13, off offset:1024
	global_store_dword v[14:15], v10, off offset:2048
	global_store_dword v[14:15], v11, off offset:3072
	global_store_dword v[16:17], v8, off
	global_store_dword v[16:17], v9, off offset:1024
	global_store_dword v[16:17], v6, off offset:2048
	global_store_dword v[16:17], v7, off offset:3072
	v_add_co_u32_e32 v6, vcc, 0x3000, v18
	s_nop 1
	v_addc_co_u32_e32 v7, vcc, 0, v19, vcc
	global_store_dword v[6:7], v4, off
	global_store_dword v[6:7], v5, off offset:1024
	global_store_dword v[6:7], v2, off offset:2048
	global_store_dword v[6:7], v3, off offset:3072

.LBB0_380:
	ds_read_b128 v[56:59], v67 offset:2304
	ds_read_b128 v[48:51], v67
	v_add_u32_e32 v73, 19, v114
	v_subrev_u32_e32 v75, 19, v113
	v_cndmask_b32_e64 v73, v73, v75, s[36:37]
	v_cmp_lt_i32_e32 vcc, -1, v73
	v_cvt_f32_u32_e32 v73, v73
	s_waitcnt lgkmcnt(1)
	v_mfma_f32_16x16x32_bf16 v[116:119], v[0:3], v[56:59], 0
	v_add_u32_e32 v110, v61, v63
	v_subrev_u32_e32 v111, 18, v113
	v_mul_f32_e64 v73, -v76, v73
	v_mfma_f32_16x16x32_bf16 v[120:123], v[8:11], v[56:59], 0
	ds_read_b128 v[56:59], v67 offset:64
	v_mul_f32_e32 v73, 0x3fb8aa3b, v73
	v_exp_f32_e32 v73, v73
	s_waitcnt lgkmcnt(1)
	v_mfma_f32_16x16x32_bf16 v[52:55], v[0:3], v[48:51], 0
	v_subrev_u32_e32 v112, 17, v113
	v_add_u32_e32 v115, -16, v113
	v_cndmask_b32_e32 v73, 0, v73, vcc
	s_waitcnt lgkmcnt(0)
	v_mfma_f32_16x16x32_bf16 v[124:127], v[4:7], v[56:59], v[52:55]
	s_add_i32 s1, s1, 1
	s_cmp_ge_i32 s1, s0
	v_mfma_f32_16x16x32_bf16 v[48:51], v[8:11], v[48:51], 0
	v_mfma_f32_16x16x32_bf16 v[52:55], v[12:15], v[56:59], v[48:51]
	s_nop 3
	v_mul_f32_e32 v75, v73, v124
	v_cvt_pk_bf16_f32 v75, v75, s0
	s_nop 0
	ds_read_b128 v[48:51], v67 offset:2368
	ds_write_b16 v110, v75 offset:63488
	v_add_u32_e32 v75, 18, v114
	v_cndmask_b32_e64 v75, v75, v111, s[36:37]
	v_cmp_lt_i32_e32 vcc, -1, v75
	v_cvt_f32_u32_e32 v75, v75
	s_waitcnt lgkmcnt(1)
	v_mfma_f32_16x16x32_bf16 v[56:59], v[4:7], v[48:51], v[116:119]
	ds_read_b128 v[128:131], v65
	ds_read_b128 v[132:135], v65 offset:4352
	ds_read_b128 v[136:139], v65 offset:8704
	ds_read_b128 v[140:143], v65 offset:13056
	v_add_u32_e32 v67, 0x1200, v67
	v_mul_f32_e64 v75, -v76, v75
	v_mul_f32_e32 v75, 0x3fb8aa3b, v75
	v_exp_f32_e32 v75, v75
	v_subrev_u32_e32 v116, 35, v113
	v_mfma_f32_16x16x32_bf16 v[48:51], v[12:15], v[48:51], v[120:123]
	v_cndmask_b32_e32 v75, 0, v75, vcc
	v_mul_f32_e32 v111, v75, v125
	v_cvt_pk_bf16_f32 v111, v111, s0
	ds_write_b16 v110, v111 offset:63568
	v_add_u32_e32 v111, 17, v114
	v_cndmask_b32_e64 v111, v111, v112, s[36:37]
	v_cmp_lt_i32_e32 vcc, -1, v111
	v_cvt_f32_u32_e32 v111, v111
	v_mul_f32_e32 v48, v73, v48
	v_cvt_pk_bf16_f32 v48, v48, s0
	ds_write_b16 v69, v48 offset:64768
	v_mul_f32_e64 v111, -v76, v111
	v_mul_f32_e32 v111, 0x3fb8aa3b, v111
	v_exp_f32_e32 v111, v111
	v_mul_f32_e32 v48, v75, v49
	v_cvt_pk_bf16_f32 v48, v48, s0
	ds_write_b16 v69, v48 offset:64848
	v_cndmask_b32_e32 v111, 0, v111, vcc
	v_mul_f32_e32 v112, v111, v126
	v_cvt_pk_bf16_f32 v112, v112, s0
	ds_write_b16 v110, v112 offset:63648
	v_add_u32_e32 v112, 16, v114
	v_cndmask_b32_e64 v112, v112, v115, s[36:37]
	v_cmp_lt_i32_e32 vcc, -1, v112
	v_cvt_f32_u32_e32 v112, v112
	v_mul_f32_e32 v48, v111, v50
	v_cvt_pk_bf16_f32 v48, v48, s0
	ds_write_b16 v69, v48 offset:64928
	v_mul_f32_e64 v112, -v76, v112
	v_mul_f32_e32 v112, 0x3fb8aa3b, v112
	v_exp_f32_e32 v112, v112
	s_nop 0
	v_cndmask_b32_e32 v112, 0, v112, vcc
	v_mul_f32_e32 v115, v112, v127
	v_cvt_pk_bf16_f32 v115, v115, s0
	ds_write_b16 v110, v115 offset:63728
	v_add_u32_e32 v115, 35, v114
	v_cndmask_b32_e64 v115, v115, v116, s[36:37]
	v_cmp_lt_i32_e32 vcc, -1, v115
	v_cvt_f32_u32_e32 v115, v115
	v_mul_f32_e32 v48, v112, v51
	v_cvt_pk_bf16_f32 v48, v48, s0
	ds_write_b16 v69, v48 offset:65008
	v_mul_f32_e64 v115, -v76, v115
	v_mul_f32_e32 v115, 0x3fb8aa3b, v115
	v_exp_f32_e32 v115, v115
	s_nop 0
	v_cndmask_b32_e32 v115, 0, v115, vcc
	v_mul_f32_e32 v56, v115, v56
	v_cvt_pk_bf16_f32 v56, v56, s0
	ds_write_b16 v69, v56 offset:63488
	v_add_u32_e32 v56, 34, v114
	v_subrev_u32_e32 v115, 34, v113
	v_cndmask_b32_e64 v56, v56, v115, s[36:37]
	v_cmp_lt_i32_e32 vcc, -1, v56
	v_cvt_f32_u32_e32 v56, v56
	v_mul_f32_e64 v56, -v76, v56
	v_mul_f32_e32 v56, 0x3fb8aa3b, v56
	v_exp_f32_e32 v56, v56
	s_nop 0
	v_cndmask_b32_e32 v56, 0, v56, vcc
	v_mul_f32_e32 v56, v56, v57
	v_cvt_pk_bf16_f32 v56, v56, s0
	ds_write_b16 v69, v56 offset:63568
	v_add_u32_e32 v56, 33, v114
	v_subrev_u32_e32 v57, 33, v113
	v_cndmask_b32_e64 v56, v56, v57, s[36:37]
	v_cmp_lt_i32_e32 vcc, -1, v56
	v_cvt_f32_u32_e32 v56, v56
	v_subrev_u32_e32 v57, 32, v113
	v_mul_f32_e64 v56, -v76, v56
	v_mul_f32_e32 v56, 0x3fb8aa3b, v56
	v_exp_f32_e32 v56, v56
	s_nop 0
	v_cndmask_b32_e32 v56, 0, v56, vcc
	v_mul_f32_e32 v56, v56, v58
	v_cvt_pk_bf16_f32 v56, v56, s0
	ds_write_b16 v69, v56 offset:63648
	v_add_u32_e32 v56, 32, v114
	v_cndmask_b32_e64 v58, v56, v57, s[36:37]
	v_cmp_lt_i32_e32 vcc, -1, v58
	v_cvt_f32_u32_e32 v58, v58
	v_mul_f32_e64 v58, -v76, v58
	v_mul_f32_e32 v58, 0x3fb8aa3b, v58
	v_exp_f32_e32 v58, v58
	s_nop 0
	v_cndmask_b32_e32 v58, 0, v58, vcc
	v_mul_f32_e32 v58, v58, v59
	v_cvt_pk_bf16_f32 v58, v58, s0
	ds_write_b16 v69, v58 offset:63728
	v_add_u32_e32 v58, 3, v114
	v_add_u32_e32 v59, -3, v113
	v_cndmask_b32_e64 v58, v58, v59, s[36:37]
	v_cmp_lt_i32_e32 vcc, -1, v58
	v_cvt_f32_u32_e32 v58, v58
	v_mul_f32_e64 v58, -v76, v58
	v_mul_f32_e32 v58, 0x3fb8aa3b, v58
	v_exp_f32_e32 v58, v58
	s_nop 0
	v_cndmask_b32_e32 v58, 0, v58, vcc
	v_mul_f32_e32 v52, v58, v52
	v_cvt_pk_bf16_f32 v52, v52, s0
	ds_write_b16 v110, v52 offset:64768
	v_add_u32_e32 v52, 2, v114
	v_add_u32_e32 v58, -2, v113
	v_cndmask_b32_e64 v52, v52, v58, s[36:37]
	v_cmp_lt_i32_e32 vcc, -1, v52
	v_cvt_f32_u32_e32 v52, v52
	v_mul_f32_e64 v52, -v76, v52
	v_mul_f32_e32 v52, 0x3fb8aa3b, v52
	v_exp_f32_e32 v52, v52
	s_nop 0
	v_cndmask_b32_e32 v52, 0, v52, vcc
	v_mul_f32_e32 v52, v52, v53
	v_cvt_pk_bf16_f32 v52, v52, s0
	ds_write_b16 v110, v52 offset:64848
	v_add_u32_e32 v52, 1, v114
	v_add_u32_e32 v53, -1, v113
	v_cndmask_b32_e64 v52, v52, v53, s[36:37]
	v_cmp_lt_i32_e32 vcc, -1, v52
	v_cvt_f32_u32_e32 v52, v52
	v_mul_f32_e64 v52, -v76, v52
	v_mul_f32_e32 v52, 0x3fb8aa3b, v52
	v_exp_f32_e32 v52, v52
	s_nop 0
	v_cndmask_b32_e32 v52, 0, v52, vcc
	v_mul_f32_e32 v52, v52, v54
	v_cvt_pk_bf16_f32 v52, v52, s0
	ds_write_b16 v110, v52 offset:64928
	v_cndmask_b32_e64 v52, v114, v113, s[36:37]
	v_cmp_lt_i32_e32 vcc, -1, v52
	v_cvt_f32_u32_e32 v52, v52
	v_mov_b32_e32 v114, v56
	v_mul_f32_e64 v52, -v76, v52
	v_mul_f32_e32 v52, 0x3fb8aa3b, v52
	v_exp_f32_e32 v52, v52
	s_nop 0
	v_cndmask_b32_e32 v52, 0, v52, vcc
	v_mul_f32_e32 v52, v52, v55
	v_cvt_pk_bf16_f32 v52, v52, s0
	ds_write_b16 v110, v52 offset:65008
	s_waitcnt lgkmcnt(0)
	ds_read_b128 v[48:51], v71 offset:63488
	ds_read_b128 v[52:55], v71 offset:64768
	s_waitcnt lgkmcnt(0)
	v_mfma_f32_16x16x32_bf16 v[20:23], v[48:51], v[128:131], v[20:23]
	v_mfma_f32_16x16x32_bf16 v[16:19], v[52:55], v[128:131], v[16:19]
	v_mfma_f32_16x16x32_bf16 v[28:31], v[48:51], v[132:135], v[28:31]
	v_mfma_f32_16x16x32_bf16 v[24:27], v[52:55], v[132:135], v[24:27]
	v_mfma_f32_16x16x32_bf16 v[44:47], v[48:51], v[136:139], v[44:47]
	v_mfma_f32_16x16x32_bf16 v[36:39], v[52:55], v[136:139], v[36:39]
	v_add_u32_e32 v65, 64, v65
	v_mfma_f32_16x16x32_bf16 v[32:35], v[48:51], v[140:143], v[32:35]
	v_mfma_f32_16x16x32_bf16 v[40:43], v[52:55], v[140:143], v[40:43]
	v_mov_b32_e32 v113, v57
	s_cbranch_scc0 .LBB0_380
